# N8 + interval header (parity, role, masks, LDS addresses) computed before the end-of-interval wait and barrier
# speedup vs baseline: 1.0208x; 1.0026x over previous
; __device__ __forceinline__ int v_st(int k, int c) { const int kk = (k & ~0xC) | ((k & 4) << 1) | ((k & 8) >> 1); return ((kk >> 3) * 4 + (c >> 5)) * 512 + ((kk & 7) * 32 + (c & 31)) * 2; }
; __device__ __forceinline__ int v_rd_base(int lane) { return ((lane & 3) << 3) | (((lane >> 2) & 3) << 6) | (((lane >> 4) & 1) << 5) | (((lane >> 5) & 1) << 8); }
; template <int LDQ, int LDK, int LDO>
; __device__ __forceinline__ void attn_pair_body(const bf16* __restrict__ Qb, const bf16* __restrict__ Kh, const bf16* __restrict__ Vh, float* __restrict__ Ob, int NT, char* lds, int tid_in) {
;   int tid_l = tid_in; asm volatile("" : "+v"(tid_l)); const int tid = tid_l, wid = __builtin_amdgcn_readfirstlane(tid >> 6), lane = tid & 63, r32 = lane & 31, hi = lane >> 5;
;   const int rg = wid & 3, vhw = wid >> 2;
;   char* V_lds = lds + AP_V; char* K_lds = lds + AP_K;
;   char* Pp = lds + AP_P + rg * 8192;
;   float* ALp = (float*)(lds + AP_AL) + rg * 64; float* Mp = (float*)(lds + AP_M) + rg * 32; unsigned* FLp = (unsigned*)(lds + AP_FL) + rg * 2; float* LXp = (float*)(lds + AP_LX) + rg * 64;
;   float m_reg = -1e30f, l_reg = 0.f; f32x16 o[4] = {}; bf16x8 qr[8];
;   const bf16* Qw = Qb + (long)(rg * QBLK + r32) * LDQ + hi * 8;
; #pragma unroll
;   for (int d0 = 0; d0 < 8; ++d0) qr[d0] = *reinterpret_cast<const bf16x8*>(Qw + d0 * 16);
;   const int sr = tid >> 4, sc = (tid & 15) * 8, vst0 = v_st(sr, sc), vst1 = v_st(32 + sr, sc);
;   const int vb0 = (int)(uintptr_t)(V_lds + vhw * 16384) + v_rd_base(lane);
;   bf16x8 ks0, ks1, vs00, vs01, vs10, vs11;
;     ...
;   KLOAD(0); asm volatile("s_waitcnt vmcnt(0)" ::: "memory"); KWRITE(0);
;   if (NT > 1) { KLOAD(KVBLK); asm volatile("s_waitcnt vmcnt(0)" ::: "memory"); KWRITE(1); }
;   if (NT > 2) KLOAD(2 * KVBLK);
;   VLOAD(0);
;   __syncthreads();
;   f32x16 p0 = f32x16{}, p1 = f32x16{};
;   if (vhw == 0) { qkt_batched(p0, p1, (const bf16*)K_lds, qr, r32, hi); }
;   __syncthreads();
; #pragma unroll 1
;   for (int j = 0; j <= NT; ++j) {
;     const int b = j & 1, pb = b ^ 1;
;     const bool prod = (j < NT) && (b == vhw);
;     if (prod) __builtin_amdgcn_s_setprio(2); else __builtin_amdgcn_s_setprio(0);
;     const bool flp = (j >= 1) && (__builtin_amdgcn_readfirstlane((int)FLp[pb]) != 0);
;     const float alp_v = ALp[pb * 32 + r32], m_v = Mp[r32];
.LBB0_1015:
	v_and_b32_e32 v5, 0xfffff0, v188
	v_lshlrev_b32_e32 v7, 1, v188
	v_and_or_b32 v5, v7, 8, v5
	v_lshrrev_b32_e32 v7, 1, v188
	v_lshrrev_b32_e32 v5, 1, v5
	v_lshrrev_b32_e32 v8, 5, v15
	v_and_b32_e32 v9, 3, v188
	s_lshl_b32 s10, s10, 2
	v_or_b32_e32 v5, v5, v8
	v_and_or_b32 v7, v7, 4, v9
	s_add_i32 s10, s10, 0
	v_lshlrev_b32_e32 v5, 9, v5
	v_lshlrev_b32_e32 v7, 6, v7
	v_and_b32_e32 v9, 48, v4
	s_add_i32 s12, s10, 0x20400
	s_lshl_b32 s10, s5, 8
	v_or3_b32 v201, v5, v7, v9
	v_and_b32_e32 v5, 0xfffff0, v189
	v_lshlrev_b32_e32 v10, 1, v189
	s_add_i32 s10, s10, 0
	v_and_or_b32 v5, v10, 8, v5
	s_lshl_b32 s9, s5, 13
	s_add_i32 s28, s10, 0x20000
	s_lshl_b32 s10, s5, 3
	v_lshrrev_b32_e32 v5, 1, v5
	v_and_b32_e32 v6, 63, v14
	s_ashr_i32 s8, s8, 8
	s_add_i32 s9, s9, 0
	s_add_i32 s10, s10, 0
	v_or_b32_e32 v5, v5, v8
	s_ashr_i32 s19, s18, 31
	s_add_i32 s15, s9, 0x18000
	s_lshl_b32 s9, s5, 6
	s_add_i32 s10, s10, 0x20600
	v_lshlrev_b32_e32 v5, 9, v5
	s_lshl_b32 s13, s8, 14
	v_lshlrev_b32_e32 v203, 4, v6
	v_or3_b32 v202, v5, v7, v9
	s_cmp_lg_u32 0, -1
	v_lshlrev_b32_e32 v5, 3, v6
	v_and_b32_e32 v7, 0xc0, v203
	v_lshlrev_b32_e32 v8, 1, v6
	s_cselect_b32 s14, 0, 0
	v_and_or_b32 v7, v5, 24, v7
	v_and_b32_e32 v8, 32, v8
	v_and_b32_e32 v5, 0x100, v5
	s_add_i32 s14, s14, s13
	v_or3_b32 v5, v7, v8, v5
	v_add_u32_e32 v211, s14, v5
	v_mov_b32_e32 v5, v3
	v_lshl_add_u64 v[182:183], s[20:21], 0, v[4:5]
	s_mov_b64 s[60:61], s[20:21]
	s_lshl_b32 s20, s8, 7
	v_lshlrev_b32_e32 v180, 2, v187
	s_add_i32 s14, s28, s20
	v_mov_b32_e32 v18, v3
	v_mov_b32_e32 v19, v3
	v_lshl_add_u64 v[184:185], s[38:39], 0, v[4:5]
	s_mov_b64 s[68:69], s[38:39]
	v_cmp_gt_u32_e64 s[38:39], 32, v6
	v_cmp_eq_u32_e64 s[40:41], 0, v6
	s_lshl_b32 s13, s8, 12
	v_add_u32_e32 v213, s14, v180
	s_lshl_b32 s14, s8, 2
	v_mov_b32_e32 v4, v3
	v_mov_b32_e32 v6, v3
	v_mov_b32_e32 v7, v3
	v_mov_b32_e32 v8, v3
	v_mov_b32_e32 v9, v3
	v_mov_b32_e32 v10, v3
	v_mov_b32_e32 v11, v3
	v_mov_b32_e32 v12, v3
	v_mov_b32_e32 v13, v3
	v_mov_b32_e32 v14, v3
	v_mov_b32_e32 v15, v3
	v_mov_b32_e32 v16, v3
	v_mov_b32_e32 v17, v3
	v_mov_b64_e32 v[66:67], v[18:19]
	v_mov_b64_e32 v[50:51], v[18:19]
	v_mov_b64_e32 v[34:35], v[18:19]
	s_mov_b32 s11, 1
	v_add_u32_e32 v212, s12, v180
	s_add_i32 s12, s4, -1
	s_add_i32 s13, s15, s13
	s_add_i32 s14, s10, s14
	v_add_u32_e32 v214, s28, v180
	v_add_u32_e32 v215, s28, v2
	v_add_u32_e32 v216, s15, v203
	v_mov_b32_e32 v218, 0
	v_mov_b32_e32 v217, 0xf149f2ca
	v_mov_b64_e32 v[64:65], v[16:17]
	v_mov_b64_e32 v[62:63], v[14:15]
	v_mov_b64_e32 v[60:61], v[12:13]
	v_mov_b64_e32 v[58:59], v[10:11]
	v_mov_b64_e32 v[56:57], v[8:9]
	v_mov_b64_e32 v[54:55], v[6:7]
	v_mov_b64_e32 v[52:53], v[4:5]
	v_mov_b64_e32 v[48:49], v[16:17]
	v_mov_b64_e32 v[46:47], v[14:15]
	v_mov_b64_e32 v[44:45], v[12:13]
	v_mov_b64_e32 v[42:43], v[10:11]
	v_mov_b64_e32 v[40:41], v[8:9]
	v_mov_b64_e32 v[38:39], v[6:7]
	v_mov_b64_e32 v[36:37], v[4:5]
	v_mov_b64_e32 v[32:33], v[16:17]
	v_mov_b64_e32 v[30:31], v[14:15]
	v_mov_b64_e32 v[28:29], v[12:13]
	v_mov_b64_e32 v[26:27], v[10:11]
	v_mov_b64_e32 v[24:25], v[8:9]
	v_mov_b64_e32 v[22:23], v[6:7]
	v_mov_b64_e32 v[20:21], v[4:5]
	v_readfirstlane_b32 s46, v186
	s_lshr_b32 s46, s46, 6
	s_lshl_b32 s32, s46, 11
	s_add_i32 s32, s32, 0x10000
	s_lshr_b32 s47, s46, 2
	s_and_b32 s29, s46, 3
	s_lshl_b32 s58, s47, 14
	s_lshl_b32 s28, s29, 12
	s_add_i32 s58, s58, s28
	v_and_b32_e32 v132, 15, v186
	v_bfe_u32 v133, v186, 4, 2
	v_xor_b32_e32 v134, v132, v133
	v_lshlrev_b32_e32 v134, 4, v134
	v_mul_u32_u24_e32 v135, 0x2400, v133
	s_mul_i32 s28, s46, 0x12000
	v_add3_u32 v172, v134, v135, s28
	v_xor_b32_e32 v134, 64, v134
	v_add3_u32 v173, v134, v135, s28
	v_add_u32_e32 v173, 0x9000, v173
	v_bfe_u32 v132, v186, 4, 1
	v_bfe_u32 v133, v186, 2, 2
	v_lshl_add_u32 v132, v132, 3, v133
	v_mul_u32_u24_e32 v132, 0x2400, v132
	v_bfe_u32 v133, v186, 5, 1
	v_lshlrev_b32_e32 v133, 6, v133
	v_and_b32_e32 v134, 3, v186
	v_lshl_add_u32 v133, v134, 4, v133
	s_mul_i32 s28, s29, 0x24000
	s_lshl_b32 s47, s47, 8
	s_add_i32 s28, s28, s47
	v_add3_u32 v174, v132, v133, s28
	s_add_u32 s74, s60, 0x90000
	s_addc_u32 s75, s61, 0
	s_sub_u32 s92, s68, 0x90000
	s_subb_u32 s93, s69, 0
	s_sub_u32 s96, s68, 0x87000
	s_subb_u32 s97, s69, 0
	s_add_i32 s65, s32, 0x4000
	s_add_i32 s77, s58, 0x8000
	s_branch .Lpa_hdr
.LBB0_1016:
	s_add_i32 s11, s11, 1
	s_cmp_eq_u32 s15, s4
	s_cbranch_scc1 .Lpa_exit
.Lpa_hdr:
	s_add_i32 s15, s11, -1
	s_and_b32 s28, s15, 1
	s_xor_b32 s21, s28, 1
	s_lshl_b32 s29, s21, 2
	s_add_i32 s29, s10, s29
	v_mov_b32_e32 v210, s29
	v_lshl_add_u32 v157, s21, 12, v216
	v_lshl_add_u32 v156, s21, 7, v214
	s_cmp_lg_u32 s15, 0
	s_cselect_b64 s[56:57], -1, 0
	s_cselect_b64 s[44:45], 0, -1
	s_cmp_eq_u32 s28, s8
	s_cselect_b64 s[52:53], -1, 0
	s_cmp_lt_i32 s15, s4
	s_cselect_b64 s[42:43], -1, 0
	s_and_b64 s[42:43], s[42:43], s[52:53]
	s_waitcnt vmcnt(0) lgkmcnt(0)
	s_barrier
	s_cbranch_scc0 .Lpa_cons
	s_setprio 2
	ds_read_b32 v210, v210
	ds_read_b32 v219, v156
	ds_read_b32 v220, v212
	s_xor_b32 s65, s65, 0x4000
	s_xor_b32 s77, s77, 0x8000
	s_add_u32 s74, s74, 0x90000
	s_addc_u32 s75, s75, 0
	s_add_u32 s92, s92, 0x90000
	s_addc_u32 s93, s93, 0
	s_add_u32 s96, s96, 0x90000
	s_addc_u32 s97, s97, 0
	s_mov_b32 m0, s65
	v_max_f32_e32 v176, v85, v85
	v_max_f32_e32 v177, v84, v84
	global_load_lds_dwordx4 v172, s[74:75]
	s_add_i32 m0, s65, 0x400
	v_max_f32_e32 v176, v177, v176
	v_max3_f32 v176, v176, v86, v87
	v_max3_f32 v176, v176, v88, v89
	v_max3_f32 v176, v176, v90, v91
	v_max3_f32 v176, v176, v92, v93
	v_max3_f32 v176, v176, v94, v95
	v_max3_f32 v176, v176, v96, v97
	v_max3_f32 v176, v176, v98, v99
	global_load_lds_dwordx4 v173, s[74:75]
	s_mov_b32 m0, s77
	v_max3_f32 v176, v176, v68, v69
	v_max3_f32 v176, v176, v70, v71
	v_max3_f32 v176, v176, v72, v73
	v_max3_f32 v176, v176, v74, v75
	v_max3_f32 v176, v176, v76, v77
	v_max3_f32 v176, v176, v78, v79
	v_max3_f32 v176, v176, v80, v81
	v_max3_f32 v176, v176, v82, v83
	global_load_lds_dwordx4 v174, s[92:93]
	s_add_i32 m0, s77, 0x380
	v_mov_b32_e32 v177, v176
	s_nop 1
	v_permlane32_swap_b32_e32 v176, v177
	v_max_f32_e32 v177, v177, v177
	v_max_f32_e32 v176, v176, v176
	s_waitcnt lgkmcnt(0)
	v_readfirstlane_b32 s29, v210
	s_cmp_lg_u32 s29, 0
	s_cselect_b64 s[62:63], -1, 0
	s_and_b64 s[62:63], s[62:63], s[56:57]
	v_cndmask_b32_e64 v217, v220, v217, s[44:45]
	v_max_f32_e32 v221, v176, v177
	v_sub_f32_e32 v176, v221, v217
	v_cmp_ge_f32_e32 vcc, s27, v176
	s_cmp_eq_u64 vcc, exec
	v_mov_b32_e32 v220, 1.0
	s_cbranch_scc0 .LBB0_1036

; #define SBAR() __builtin_amdgcn_sched_barrier(0)
; __device__ __forceinline__ int crow(int r, int hi) { return (r & 3) + 8 * (r >> 2) + 4 * hi; }
; #define KLOAD(k0) do { ks0 = *reinterpret_cast<const bf16x8*>(&Kh[(long)((k0) + sr) * LDK + sc]); ks1 = *reinterpret_cast<const bf16x8*>(&Kh[(long)((k0) + 32 + sr) * LDK + sc]); } while (0)
; template <int LDQ, int LDK, int LDO>
; __device__ __forceinline__ void attn_pair_body(const bf16* __restrict__ Qb, const bf16* __restrict__ Kh, const bf16* __restrict__ Vh, float* __restrict__ Ob, int NT, char* lds, int tid_in) {
;     ...
;     const float alp_v = ALp[pb * 32 + r32], m_v = Mp[r32];
;     const bf16x8 a0 = *reinterpret_cast<const bf16x8*>(Pp + pb * 4096 + 0 * 1024 + lane * 16), a1 = *reinterpret_cast<const bf16x8*>(Pp + pb * 4096 + 1 * 1024 + lane * 16);
;     const bf16x8 a2 = *reinterpret_cast<const bf16x8*>(Pp + pb * 4096 + 2 * 1024 + lane * 16), a3 = *reinterpret_cast<const bf16x8*>(Pp + pb * 4096 + 3 * 1024 + lane * 16);
;     SBAR();
;     KWRITE(b);
;     VWRITE(b);
;     { const int tk = j + 3 < NT ? j + 3 : NT - 1, tv = j + 1 < NT ? j + 1 : NT - 1; KLOAD(tk * KVBLK); VLOAD(tv * KVBLK); }
;     SBAR();
;     if (prod) {
;       if (flp) l_reg *= alp_v;
;       if (j >= 1) m_reg = m_v;
;       float mn, al; bf16x8 pa0, pa1, pa2, pa3;
;       partialSM(p0, p1, m_reg, mn, al);
;       finishSM(p0, p1, al, l_reg, pa0, pa1, pa2, pa3);
;       *reinterpret_cast<bf16x8*>(Pp + b * 4096 + 0 * 1024 + lane * 16) = pa0; *reinterpret_cast<bf16x8*>(Pp + b * 4096 + 1 * 1024 + lane * 16) = pa1;
;       *reinterpret_cast<bf16x8*>(Pp + b * 4096 + 2 * 1024 + lane * 16) = pa2; *reinterpret_cast<bf16x8*>(Pp + b * 4096 + 3 * 1024 + lane * 16) = pa3;
;       if (hi == 0) { ALp[b * 32 + r32] = al; Mp[r32] = m_reg; }
;       const unsigned fl = __any(al < 1.f) ? 1u : 0u;
;       if (lane == 0) FLp[b] = fl;
;       SBAR();
;     }
;     if (j >= 1) {
;       if (flp) {
; #pragma unroll
;         for (int d = 0; d < 4; ++d)
; #pragma unroll
;           for (int r = 0; r < 16; ++r) o[d][r] *= ALp[pb * 32 + crow(r, hi)];
;       }
;       pv_batched(o, vb0 + pb * 32768, a0, a1, a2, a3);
;     }
;     if (!prod && j + 1 < NT) { SBAR(); qkt_batched(p0, p1, (const bf16*)(K_lds + pb * 16384), qr, r32, hi); SBAR(); }
.Lpa_cons:
	s_setprio 0
	ds_read_b32 v210, v210
	ds_read_b128 v[168:171], v157
	ds_read_b128 v[164:167], v157 offset:1024
	ds_read_b128 v[160:163], v157 offset:2048
	ds_read_b128 v[156:159], v157 offset:3072
	v_lshl_add_u32 v219, s21, 15, v211
	ds_read_b64_tr_b16 v[220:221], v219 offset:0
	ds_read_b64_tr_b16 v[222:223], v219 offset:0x800
	ds_read_b64_tr_b16 v[224:225], v219 offset:0x1000
	ds_read_b64_tr_b16 v[226:227], v219 offset:0x1800
	ds_read_b64_tr_b16 v[234:235], v219 offset:0x2000
	ds_read_b64_tr_b16 v[236:237], v219 offset:0x2800
	ds_read_b64_tr_b16 v[238:239], v219 offset:0x3000
	ds_read_b64_tr_b16 v[240:241], v219 offset:0x3800
	ds_read_b64_tr_b16 v[242:243], v219 offset:0x200
	ds_read_b64_tr_b16 v[244:245], v219 offset:0xa00
	ds_read_b64_tr_b16 v[246:247], v219 offset:0x1200
	ds_read_b64_tr_b16 v[248:249], v219 offset:0x1a00
	ds_read_b64_tr_b16 v[176:177], v219 offset:0x2200
	ds_read_b64_tr_b16 v[178:179], v219 offset:0x2a00
	ds_read_b64_tr_b16 v[228:229], v219 offset:0x3200
	ds_read_b64_tr_b16 v[230:231], v219 offset:0x3a00
	s_waitcnt lgkmcnt(15)
	v_readfirstlane_b32 s29, v210
	s_cmp_lg_u32 s29, 0
	s_cselect_b64 s[62:63], -1, 0
	s_and_b64 s[62:63], s[62:63], s[56:57]
	s_andn2_b64 vcc, exec, s[56:57]
	s_cbranch_vccnz .Lpa_cons_j0
	s_lshl_b32 s28, s21, 5
	s_andn2_b64 vcc, exec, s[62:63]
	s_cbranch_vccnz .Lpa_cons_pv
	v_lshl_add_u32 v148, s28, 2, v215
	ds_read_b128 v[132:135], v148 offset:96
	ds_read_b128 v[136:139], v148 offset:64
	ds_read_b128 v[140:143], v148 offset:32
	ds_read_b128 v[144:147], v148
	s_waitcnt lgkmcnt(3)
	v_pk_mul_f32 v[18:19], v[18:19], v[134:135]
	s_waitcnt lgkmcnt(2)
	v_pk_mul_f32 v[14:15], v[14:15], v[138:139]
	s_waitcnt lgkmcnt(1)
	v_pk_mul_f32 v[10:11], v[10:11], v[142:143]
	s_waitcnt lgkmcnt(0)
	v_pk_mul_f32 v[6:7], v[6:7], v[146:147]
	v_pk_mul_f32 v[16:17], v[16:17], v[132:133]
	v_pk_mul_f32 v[12:13], v[12:13], v[136:137]
	v_pk_mul_f32 v[8:9], v[8:9], v[140:141]
	v_pk_mul_f32 v[4:5], v[4:5], v[144:145]
	v_pk_mul_f32 v[66:67], v[66:67], v[134:135]
	v_pk_mul_f32 v[62:63], v[62:63], v[138:139]
	v_pk_mul_f32 v[58:59], v[58:59], v[142:143]
	v_pk_mul_f32 v[54:55], v[54:55], v[146:147]
	v_pk_mul_f32 v[64:65], v[64:65], v[132:133]
	v_pk_mul_f32 v[60:61], v[60:61], v[136:137]
	v_pk_mul_f32 v[56:57], v[56:57], v[140:141]
	v_pk_mul_f32 v[52:53], v[52:53], v[144:145]
	v_pk_mul_f32 v[50:51], v[50:51], v[134:135]
	v_pk_mul_f32 v[46:47], v[46:47], v[138:139]
	v_pk_mul_f32 v[42:43], v[42:43], v[142:143]
	v_pk_mul_f32 v[38:39], v[38:39], v[146:147]
	v_pk_mul_f32 v[48:49], v[48:49], v[132:133]
	v_pk_mul_f32 v[44:45], v[44:45], v[136:137]
	v_pk_mul_f32 v[40:41], v[40:41], v[140:141]
	v_pk_mul_f32 v[36:37], v[36:37], v[144:145]
	v_pk_mul_f32 v[34:35], v[34:35], v[134:135]
	v_pk_mul_f32 v[30:31], v[30:31], v[138:139]
	v_pk_mul_f32 v[26:27], v[26:27], v[142:143]
	v_pk_mul_f32 v[22:23], v[22:23], v[146:147]
	v_pk_mul_f32 v[32:33], v[32:33], v[132:133]
	v_pk_mul_f32 v[28:29], v[28:29], v[136:137]
	v_pk_mul_f32 v[24:25], v[24:25], v[140:141]
	v_pk_mul_f32 v[20:21], v[20:21], v[144:145]

; __device__ __forceinline__ void partialSM(f32x16& p0, f32x16& p1, float& m_reg, float& mn, float& alpha) {
;     ...
;   if (__builtin_expect(__all(pmax - m_reg <= THR / SCALE), 1)) { mn = m_reg; alpha = 1.f; }
;   else { mn = fmaxf(m_reg, pmax); alpha = __builtin_amdgcn_exp2f((m_reg - mn) * C); m_reg = mn; }
; template <int LDQ, int LDK, int LDO>
; __device__ __forceinline__ void attn_pair_body(const bf16* __restrict__ Qb, const bf16* __restrict__ Kh, const bf16* __restrict__ Vh, float* __restrict__ Ob, int NT, char* lds, int tid_in) {
;     ...
;     __syncthreads();
;   }
;   __builtin_amdgcn_s_setprio(0);
;   if (hi == 0) LXp[vhw * 32 + r32] = l_reg;
.LBB0_1036:
	v_max_f32_e32 v176, v221, v221
	v_max_f32_e32 v177, v217, v217
	v_max_f32_e32 v176, v177, v176
	v_sub_f32_e32 v177, v217, v176
	v_mul_f32_e32 v177, 0x3e0293ee, v177
	v_exp_f32_e32 v220, v177
	v_mov_b32_e32 v217, v176
	s_branch .LBB0_1025
.Lpa_exit:
	s_waitcnt vmcnt(0) lgkmcnt(0)
	s_barrier
.LBB0_1037:
	v_mov_b32_e32 v210, 0x5800
	v_mov_b32_e32 v172, v175
	v_mov_b32_e32 v173, v175
	v_mov_b32_e32 v174, v175
	v_mov_b64_e32 v[246:247], v[174:175]
	v_mov_b64_e32 v[248:249], v[174:175]
	s_lshl_b32 s8, s9, 2
	s_add_i32 s8, s8, 0
	s_mov_b32 s29, s85
	s_add_i32 s8, s8, 0x20640
	s_setprio 0
	s_and_saveexec_b64 s[40:41], s[38:39]
	s_cbranch_execz .LBB0_997
	s_add_i32 s9, s8, s20
	v_lshl_add_u32 v68, v187, 2, s9
	ds_write_b32 v68, v218
	s_branch .LBB0_997
